# scan seg-1 dsum loads issued together; pool epilogue scale loads hoisted (stores stay in flight); gnorm weights loaded once per wave
# speedup vs baseline: 1.0936x; 1.0086x over previous
; DI int otid() { int t = threadIdx.x; asm volatile("" : "+v"(t)); return t; }
; DI void gnorm_phase(bf16_t* P, const float* nw, bool dry) {
;   const int tid = otid(), lane = tid & 63, wave = tid >> 6;
;   const int stride = gridDim.x * 8;
;   for (int rg0 = blockIdx.x * 8 + wave; rg0 < T * 4; rg0 += stride * 4) {
;     u32x4 r[4];
; #pragma unroll
;     for (int k = 0; k < 4; ++k) { const int rg = rg0 + k * stride; const int rgc = (rg < T * 4) ? rg : rg0; r[k] = *(const u32x4*)(P + (size_t)(rgc >> 2) * 5120 + (rgc & 3) * 512 + lane * 8); }
; #pragma unroll
;     for (int k = 0; k < 4; ++k) {
;       const int rg = rg0 + k * stride;
;       if (rg < T * 4) {
;         const int t = rg >> 2, g = rg & 3;
;         float f[8]; unpack8(r[k], f);
;         float ss = 0.f;
; #pragma unroll
;         for (int e = 0; e < 8; ++e) ss += f[e] * f[e];
;         ss = wave_sum(ss);
;         const float rstd = rsqrtf(ss * (1.f / 512.f) + 1e-5f);
;         const f32x4 w0 = *(const f32x4*)(nw + g * 512 + lane * 8), w1 = *(const f32x4*)(nw + g * 512 + lane * 8 + 4);
.LBB0_992:
	s_and_b64 vcc, exec, s[48:49]
	s_cbranch_vccz .LBB0_1002
	v_mov_b32_e32 v0, v200
	v_readlane_b32 s0, v252, 41
	s_waitcnt vmcnt(0)
	v_ashrrev_i32_e32 v3, 6, v0
	v_add_u32_e32 v2, s0, v3
	s_mov_b32 s0, 0x10000
	v_cmp_gt_i32_e32 vcc, s0, v2
	s_and_saveexec_b64 s[30:31], vcc
	s_cbranch_execz .LBB0_1006
	v_readlane_b32 s0, v252, 4
	v_readlane_b32 s1, v252, 5
	s_load_dword s40, s[0:1], 0x0
	v_readlane_b32 s0, v255, 18
	s_lshl_b32 s34, s0, 11
	v_readlane_b32 s4, v253, 34
	v_lshlrev_b32_e32 v0, 3, v0
	s_lshl_b64 s[0:1], s[34:35], 2
	s_waitcnt lgkmcnt(0)
	s_lshl_b32 s28, s40, 3
	v_readlane_b32 s14, v253, 44
	v_and_b32_e32 v4, 0x1f8, v0
	v_readlane_b32 s5, v253, 35
	v_readlane_b32 s6, v253, 36
	v_readlane_b32 s7, v253, 37
	v_readlane_b32 s8, v253, 38
	v_readlane_b32 s9, v253, 39
	v_readlane_b32 s10, v253, 40
	v_readlane_b32 s11, v253, 41
	v_readlane_b32 s12, v253, 42
	v_readlane_b32 s13, v253, 43
	v_readlane_b32 s15, v253, 45
	v_readlane_b32 s16, v253, 46
	v_readlane_b32 s17, v253, 47
	v_readlane_b32 s18, v253, 48
	v_readlane_b32 s19, v253, 49
	s_add_u32 s0, s14, s0
	s_addc_u32 s1, s15, s1
	v_lshlrev_b32_e32 v0, 2, v4
	v_readlane_b32 s4, v253, 16
	v_lshl_add_u64 v[14:15], s[0:1], 0, v[0:1]
	v_lshlrev_b32_e32 v0, 1, v4
	v_readlane_b32 s18, v253, 30
	v_readlane_b32 s19, v253, 31
	v_xor_b32_e32 v5, 32, v204
	v_readlane_b32 s0, v255, 4
	v_lshl_add_u64 v[16:17], s[18:19], 0, v[0:1]
	v_and_b32_e32 v0, 64, v204
	v_add_u32_e32 v0, 64, v0
	v_cmp_lt_i32_e32 vcc, v5, v0
	s_lshl_b32 s34, s40, 4
	s_mul_i32 s37, s40, 24
	v_cndmask_b32_e32 v5, v204, v5, vcc
	v_lshlrev_b32_e32 v24, 2, v5
	v_xor_b32_e32 v5, 16, v204
	v_cmp_lt_i32_e32 vcc, v5, v0
	v_lshl_add_u32 v30, v3, 9, s0
	s_lshl_b32 s48, s40, 14
	v_cndmask_b32_e32 v5, v204, v5, vcc
	v_lshlrev_b32_e32 v25, 2, v5
	v_xor_b32_e32 v5, 8, v204
	v_cmp_lt_i32_e32 vcc, v5, v0
	s_mov_b64 s[44:45], 0
	v_lshlrev_b32_e32 v18, 1, v4
	v_cndmask_b32_e32 v5, v204, v5, vcc
	v_lshlrev_b32_e32 v26, 2, v5
	v_xor_b32_e32 v5, 4, v204
	v_cmp_lt_i32_e32 vcc, v5, v0
	v_readlane_b32 s5, v253, 17
	v_readlane_b32 s6, v253, 18
	v_cndmask_b32_e32 v5, v204, v5, vcc
	v_lshlrev_b32_e32 v27, 2, v5
	v_xor_b32_e32 v5, 2, v204
	v_cmp_lt_i32_e32 vcc, v5, v0
	v_readlane_b32 s7, v253, 19
	v_readlane_b32 s8, v253, 20
	v_cndmask_b32_e32 v5, v204, v5, vcc
	v_lshlrev_b32_e32 v28, 2, v5
	v_xor_b32_e32 v5, 1, v204
	v_cmp_lt_i32_e32 vcc, v5, v0
	v_readlane_b32 s9, v253, 21
	v_readlane_b32 s10, v253, 22
	v_cndmask_b32_e32 v0, v204, v5, vcc
	v_lshlrev_b32_e32 v29, 2, v0
	v_readlane_b32 s11, v253, 23
	v_readlane_b32 s12, v253, 24
	v_readlane_b32 s13, v253, 25
	v_readlane_b32 s14, v253, 26
	v_readlane_b32 s15, v253, 27
	v_readlane_b32 s16, v253, 28
	v_readlane_b32 s17, v253, 29
	v_and_b32_e32 v0, 0x600, v30
	v_lshlrev_b32_e32 v0, 2, v0
	v_lshl_add_u64 v[58:59], v[14:15], 0, v[0:1]
	global_load_dwordx4 v[60:63], v[58:59], off
	global_load_dwordx4 v[64:67], v[58:59], off offset:16
	s_branch .LBB0_996

; DI u32x4 pack8(const float (&f)[8]) { u32x4 r; r[0] = pk2(f[0], f[1]); r[1] = pk2(f[2], f[3]); r[2] = pk2(f[4], f[5]); r[3] = pk2(f[6], f[7]); return r; }
; DI void gnorm_phase(bf16_t* P, const float* nw, bool dry) {
;     ...
;   for (int rg0 = blockIdx.x * 8 + wave; rg0 < T * 4; rg0 += stride * 4) {
;     u32x4 r[4];
; #pragma unroll
;     for (int k = 0; k < 4; ++k) { const int rg = rg0 + k * stride; const int rgc = (rg < T * 4) ? rg : rg0; r[k] = *(const u32x4*)(P + (size_t)(rgc >> 2) * 5120 + (rgc & 3) * 512 + lane * 8); }
; #pragma unroll
;     for (int k = 0; k < 4; ++k) {
;       const int rg = rg0 + k * stride;
;       if (rg < T * 4) {
;         const int t = rg >> 2, g = rg & 3;
;         float f[8]; unpack8(r[k], f);
;         float ss = 0.f;
; #pragma unroll
;         for (int e = 0; e < 8; ++e) ss += f[e] * f[e];
;         ss = wave_sum(ss);
;         const float rstd = rsqrtf(ss * (1.f / 512.f) + 1e-5f);
;         const f32x4 w0 = *(const f32x4*)(nw + g * 512 + lane * 8), w1 = *(const f32x4*)(nw + g * 512 + lane * 8 + 4);
;         f[0] *= rstd * w0[0]; f[1] *= rstd * w0[1]; f[2] *= rstd * w0[2]; f[3] *= rstd * w0[3];
;         f[4] *= rstd * w1[0]; f[5] *= rstd * w1[1]; f[6] *= rstd * w1[2]; f[7] *= rstd * w1[3];
;         if (!dry) *(u32x4*)(P + (size_t)t * 5120 + g * 512 + lane * 8) = pack8(f);
.LBB0_996:
	v_add_u32_e32 v31, s28, v2
	s_mov_b32 s49, 0x10000
	v_cmp_gt_i32_e64 s[40:41], s49, v31
	v_readlane_b32 s4, v253, 16
	v_readlane_b32 s18, v253, 30
	v_cndmask_b32_e64 v0, v2, v31, s[40:41]
	v_readlane_b32 s19, v253, 31
	v_ashrrev_i32_e32 v6, 2, v0
	v_lshlrev_b32_e32 v0, 10, v0
	v_mov_b64_e32 v[4:5], s[18:19]
	v_mad_i64_i32 v[6:7], s[0:1], v6, s96, v[4:5]
	v_add_u32_e32 v33, s34, v2
	v_and_b32_e32 v0, 0xc00, v0
	v_cmp_gt_i32_e64 s[0:1], s49, v33
	v_lshl_add_u64 v[6:7], v[6:7], 0, v[0:1]
	v_add_u32_e32 v32, s37, v2
	v_cndmask_b32_e64 v0, v2, v33, s[0:1]
	v_ashrrev_i32_e32 v8, 2, v0
	v_lshlrev_b32_e32 v0, 10, v0
	v_mad_i64_i32 v[8:9], s[42:43], v8, s96, v[4:5]
	v_and_b32_e32 v0, 0xc00, v0
	v_cmp_gt_i32_e32 vcc, s49, v32
	v_lshl_add_u64 v[8:9], v[8:9], 0, v[0:1]
	v_and_b32_e32 v3, 0x600, v30
	v_cndmask_b32_e32 v0, v2, v32, vcc
	v_ashrrev_i32_e32 v10, 2, v0
	v_lshlrev_b32_e32 v0, 10, v0
	v_mad_i64_i32 v[10:11], s[42:43], v10, s96, v[4:5]
	v_and_b32_e32 v0, 0xc00, v0
	v_lshl_add_u64 v[10:11], v[10:11], 0, v[0:1]
	v_lshlrev_b32_e32 v0, 2, v3
	v_ashrrev_i32_e32 v56, 2, v2
	v_lshl_add_u64 v[20:21], v[14:15], 0, v[0:1]
	v_lshlrev_b32_e32 v0, 1, v3
	v_mad_i64_i32 v[2:3], s[42:43], v56, s96, v[4:5]
	v_mov_b32_e32 v19, v1
	v_lshl_add_u64 v[2:3], v[2:3], 0, v[0:1]
	v_lshl_add_u64 v[2:3], v[2:3], 0, v[18:19]
	global_load_dwordx4 v[34:37], v[2:3], off
	v_lshl_add_u64 v[2:3], v[6:7], 0, v[18:19]
	v_lshl_add_u64 v[4:5], v[8:9], 0, v[18:19]
	v_lshl_add_u64 v[22:23], v[10:11], 0, v[18:19]
	global_load_dwordx4 v[10:13], v[2:3], off
	global_load_dwordx4 v[6:9], v[4:5], off
	s_nop 0
	global_load_dwordx4 v[2:5], v[22:23], off
	s_mov_b32 s4, 0x800000
	v_readlane_b32 s5, v253, 17
	v_readlane_b32 s6, v253, 18
	v_readlane_b32 s7, v253, 19
	v_readlane_b32 s8, v253, 20
	v_readlane_b32 s9, v253, 21
	v_readlane_b32 s10, v253, 22
	v_readlane_b32 s11, v253, 23
	v_readlane_b32 s12, v253, 24
	v_readlane_b32 s13, v253, 25
	v_readlane_b32 s14, v253, 26
	v_readlane_b32 s15, v253, 27
	v_readlane_b32 s16, v253, 28
	v_readlane_b32 s17, v253, 29
	s_waitcnt vmcnt(3)
	v_lshlrev_b32_e32 v50, 16, v34
	v_and_b32_e32 v51, 0xffff0000, v34
	v_lshlrev_b32_e32 v46, 16, v37
	v_and_b32_e32 v47, 0xffff0000, v37
	v_lshlrev_b32_e32 v48, 16, v36
	v_and_b32_e32 v49, 0xffff0000, v36
	v_lshlrev_b32_e32 v36, 16, v35
	v_and_b32_e32 v37, 0xffff0000, v35
	v_pk_mul_f32 v[54:55], v[50:51], v[50:51]
	v_pk_mul_f32 v[52:53], v[36:37], v[36:37]
	v_add_f32_e32 v19, v54, v55
	v_add_f32_e32 v19, v52, v19
	v_pk_mul_f32 v[34:35], v[48:49], v[48:49]
	v_add_f32_e32 v19, v53, v19
	v_add_f32_e32 v19, v34, v19
	v_pk_mul_f32 v[22:23], v[46:47], v[46:47]
	v_add_f32_e32 v19, v35, v19
	v_add_f32_e32 v19, v22, v19
	v_add_f32_e32 v19, v23, v19
	ds_bpermute_b32 v22, v24, v19
	s_waitcnt lgkmcnt(0)
	v_add_f32_e32 v19, v19, v22
	ds_bpermute_b32 v22, v25, v19
	s_waitcnt lgkmcnt(0)
	v_add_f32_e32 v19, v19, v22
	ds_bpermute_b32 v22, v26, v19
	s_waitcnt lgkmcnt(0)
	v_add_f32_e32 v19, v19, v22
	ds_bpermute_b32 v22, v27, v19
	s_waitcnt lgkmcnt(0)
	v_add_f32_e32 v19, v19, v22
	ds_bpermute_b32 v22, v28, v19
	s_waitcnt lgkmcnt(0)
	v_add_f32_e32 v19, v19, v22
	ds_bpermute_b32 v22, v29, v19
	s_waitcnt lgkmcnt(0)
	v_add_f32_e32 v19, v19, v22
	v_fmamk_f32 v19, v19, 0x3b000000, v201
	v_mul_f32_e32 v22, 0x4b800000, v19
	v_cmp_gt_f32_e64 s[42:43], s4, v19
	s_nop 1
	v_cndmask_b32_e64 v19, v19, v22, s[42:43]
	v_rsq_f32_e32 v19, v19
	v_lshl_add_u64 v[22:23], v[16:17], 0, v[0:1]
	v_mul_f32_e32 v0, 0x45800000, v19
	v_cndmask_b32_e64 v0, v19, v0, s[42:43]
	v_pk_mul_f32 v[34:35], v[60:61], v[0:1] op_sel_hi:[1,0]
	v_pk_mul_f32 v[38:39], v[62:63], v[0:1] op_sel_hi:[1,0]
	v_pk_mul_f32 v[40:41], v[64:65], v[0:1] op_sel_hi:[1,0]
	v_pk_mul_f32 v[42:43], v[66:67], v[0:1] op_sel_hi:[1,0]
	v_pk_mul_f32 v[34:35], v[34:35], v[50:51]
	v_pk_mul_f32 v[36:37], v[38:39], v[36:37]
	v_pk_mul_f32 v[38:39], v[40:41], v[48:49]
	v_pk_mul_f32 v[40:41], v[42:43], v[46:47]
	v_cvt_pk_bf16_f32 v34, v34, v35
	v_cvt_pk_bf16_f32 v35, v36, v37
	v_cvt_pk_bf16_f32 v36, v38, v39
	v_cvt_pk_bf16_f32 v37, v40, v41
	v_mad_i64_i32 v[38:39], s[42:43], v56, s96, v[22:23]
	global_store_dwordx4 v[38:39], v[34:37], off
	s_and_saveexec_b64 s[42:43], s[40:41]
	s_cbranch_execnz .LBB0_999
	s_or_b64 exec, exec, s[42:43]
	s_and_saveexec_b64 s[40:41], s[0:1]
	s_cbranch_execnz .LBB0_1000

; DI u32x4 pack8(const float (&f)[8]) { u32x4 r; r[0] = pk2(f[0], f[1]); r[1] = pk2(f[2], f[3]); r[2] = pk2(f[4], f[5]); r[3] = pk2(f[6], f[7]); return r; }
; DI void gnorm_phase(bf16_t* P, const float* nw, bool dry) {
;     ...
; #pragma unroll
;     for (int k = 0; k < 4; ++k) {
;       const int rg = rg0 + k * stride;
;       if (rg < T * 4) {
;         const int t = rg >> 2, g = rg & 3;
;         float f[8]; unpack8(r[k], f);
;         float ss = 0.f;
; #pragma unroll
;         for (int e = 0; e < 8; ++e) ss += f[e] * f[e];
;         ss = wave_sum(ss);
;         const float rstd = rsqrtf(ss * (1.f / 512.f) + 1e-5f);
;         const f32x4 w0 = *(const f32x4*)(nw + g * 512 + lane * 8), w1 = *(const f32x4*)(nw + g * 512 + lane * 8 + 4);
;         f[0] *= rstd * w0[0]; f[1] *= rstd * w0[1]; f[2] *= rstd * w0[2]; f[3] *= rstd * w0[3];
;         f[4] *= rstd * w1[0]; f[5] *= rstd * w1[1]; f[6] *= rstd * w1[2]; f[7] *= rstd * w1[3];
;         if (!dry) *(u32x4*)(P + (size_t)t * 5120 + g * 512 + lane * 8) = pack8(f);
.LBB0_999:
	s_waitcnt vmcnt(3)
	v_lshlrev_b32_e32 v46, 16, v10
	v_and_b32_e32 v47, 0xffff0000, v10
	v_lshlrev_b32_e32 v42, 16, v13
	v_and_b32_e32 v43, 0xffff0000, v13
	v_lshlrev_b32_e32 v44, 16, v12
	v_and_b32_e32 v45, 0xffff0000, v12
	v_lshlrev_b32_e32 v12, 16, v11
	v_and_b32_e32 v13, 0xffff0000, v11
	v_pk_mul_f32 v[52:53], v[46:47], v[46:47]
	v_pk_mul_f32 v[50:51], v[12:13], v[12:13]
	v_add_f32_e32 v0, v52, v53
	v_add_f32_e32 v0, v50, v0
	v_pk_mul_f32 v[48:49], v[44:45], v[44:45]
	v_add_f32_e32 v0, v51, v0
	v_add_f32_e32 v0, v48, v0
	v_pk_mul_f32 v[10:11], v[42:43], v[42:43]
	v_add_f32_e32 v0, v49, v0
	v_add_f32_e32 v0, v10, v0
	v_add_f32_e32 v0, v11, v0
	ds_bpermute_b32 v10, v24, v0
	v_ashrrev_i32_e32 v19, 2, v31
	s_waitcnt lgkmcnt(0)
	v_add_f32_e32 v0, v0, v10
	ds_bpermute_b32 v10, v25, v0
	s_waitcnt lgkmcnt(0)
	v_add_f32_e32 v0, v0, v10
	ds_bpermute_b32 v10, v26, v0
	s_waitcnt lgkmcnt(0)
	v_add_f32_e32 v0, v0, v10
	ds_bpermute_b32 v10, v27, v0
	s_waitcnt lgkmcnt(0)
	v_add_f32_e32 v0, v0, v10
	ds_bpermute_b32 v10, v28, v0
	s_waitcnt lgkmcnt(0)
	v_add_f32_e32 v0, v0, v10
	ds_bpermute_b32 v10, v29, v0
	s_waitcnt lgkmcnt(0)
	v_add_f32_e32 v0, v0, v10
	v_fmamk_f32 v0, v0, 0x3b000000, v201
	v_mul_f32_e32 v10, 0x4b800000, v0
	v_cmp_gt_f32_e64 s[40:41], s4, v0
	s_nop 1
	v_cndmask_b32_e64 v0, v0, v10, s[40:41]
	v_rsq_f32_e32 v0, v0
	s_nop 0
	v_mul_f32_e32 v10, 0x45800000, v0
	v_cndmask_b32_e64 v0, v0, v10, s[40:41]
	v_pk_mul_f32 v[10:11], v[60:61], v[0:1] op_sel_hi:[1,0]
	v_pk_mul_f32 v[34:35], v[62:63], v[0:1] op_sel_hi:[1,0]
	v_pk_mul_f32 v[36:37], v[64:65], v[0:1] op_sel_hi:[1,0]
	v_pk_mul_f32 v[38:39], v[66:67], v[0:1] op_sel_hi:[1,0]
	v_pk_mul_f32 v[10:11], v[10:11], v[46:47]
	v_pk_mul_f32 v[12:13], v[34:35], v[12:13]
	v_pk_mul_f32 v[34:35], v[36:37], v[44:45]
	v_pk_mul_f32 v[36:37], v[38:39], v[42:43]
	v_cvt_pk_bf16_f32 v10, v10, v11
	v_cvt_pk_bf16_f32 v11, v12, v13
	v_cvt_pk_bf16_f32 v12, v34, v35
	v_cvt_pk_bf16_f32 v13, v36, v37
	v_mad_i64_i32 v[34:35], s[40:41], v19, s96, v[22:23]
	global_store_dwordx4 v[34:35], v[10:13], off
	s_or_b64 exec, exec, s[42:43]
	s_and_saveexec_b64 s[40:41], s[0:1]
	s_cbranch_execz .LBB0_998
.LBB0_1000:
	s_waitcnt vmcnt(3)
	v_lshlrev_b32_e32 v38, 16, v6
	v_and_b32_e32 v39, 0xffff0000, v6
	v_lshlrev_b32_e32 v6, 16, v7
	v_and_b32_e32 v7, 0xffff0000, v7
	v_pk_mul_f32 v[48:49], v[38:39], v[38:39]
	v_pk_mul_f32 v[46:47], v[6:7], v[6:7]
	v_add_f32_e32 v0, v48, v49
	v_lshlrev_b32_e32 v40, 16, v8
	v_and_b32_e32 v41, 0xffff0000, v8
	v_add_f32_e32 v0, v46, v0
	v_pk_mul_f32 v[44:45], v[40:41], v[40:41]
	v_add_f32_e32 v0, v47, v0
	v_lshlrev_b32_e32 v8, 16, v9
	v_and_b32_e32 v9, 0xffff0000, v9
	v_add_f32_e32 v0, v44, v0
	v_pk_mul_f32 v[42:43], v[8:9], v[8:9]
	v_add_f32_e32 v0, v45, v0
	v_add_f32_e32 v0, v42, v0
	v_add_f32_e32 v0, v43, v0
	ds_bpermute_b32 v19, v24, v0
	s_mov_b32 s0, 0x800000
	s_waitcnt lgkmcnt(0)
	v_add_f32_e32 v0, v0, v19
	ds_bpermute_b32 v19, v25, v0
	s_waitcnt lgkmcnt(0)
	v_add_f32_e32 v0, v0, v19
	ds_bpermute_b32 v19, v26, v0
	s_waitcnt lgkmcnt(0)
	v_add_f32_e32 v0, v0, v19
	ds_bpermute_b32 v19, v27, v0
	s_waitcnt lgkmcnt(0)
	v_add_f32_e32 v0, v0, v19
	ds_bpermute_b32 v19, v28, v0
	s_waitcnt lgkmcnt(0)
	v_add_f32_e32 v0, v0, v19
	ds_bpermute_b32 v19, v29, v0
	s_waitcnt lgkmcnt(0)
	v_add_f32_e32 v0, v0, v19
	v_fmamk_f32 v0, v0, 0x3b000000, v201
	v_mul_f32_e32 v19, 0x4b800000, v0
	v_cmp_gt_f32_e64 s[0:1], s0, v0
	s_nop 1
	v_cndmask_b32_e64 v0, v0, v19, s[0:1]
	v_rsq_f32_e32 v0, v0
	v_ashrrev_i32_e32 v19, 2, v33
	v_mul_f32_e32 v33, 0x45800000, v0
	v_cndmask_b32_e64 v0, v0, v33, s[0:1]
	v_pk_mul_f32 v[10:11], v[60:61], v[0:1] op_sel_hi:[1,0]
	v_pk_mul_f32 v[12:13], v[62:63], v[0:1] op_sel_hi:[1,0]
	v_pk_mul_f32 v[34:35], v[64:65], v[0:1] op_sel_hi:[1,0]
	v_pk_mul_f32 v[36:37], v[66:67], v[0:1] op_sel_hi:[1,0]
	v_pk_mul_f32 v[10:11], v[10:11], v[38:39]
	v_pk_mul_f32 v[12:13], v[12:13], v[6:7]
	v_pk_mul_f32 v[34:35], v[34:35], v[40:41]
	v_pk_mul_f32 v[36:37], v[36:37], v[8:9]
	v_cvt_pk_bf16_f32 v6, v10, v11
	v_cvt_pk_bf16_f32 v7, v12, v13
	v_cvt_pk_bf16_f32 v8, v34, v35
	v_cvt_pk_bf16_f32 v9, v36, v37
	v_mad_i64_i32 v[10:11], s[0:1], v19, s96, v[22:23]
	global_store_dwordx4 v[10:11], v[6:9], off
	s_or_b64 exec, exec, s[40:41]
	s_and_saveexec_b64 s[0:1], vcc
	s_cbranch_execz .LBB0_995
.LBB0_1001:
	s_waitcnt vmcnt(3)
	v_lshlrev_b32_e32 v20, 16, v2
	v_and_b32_e32 v21, 0xffff0000, v2
	v_lshlrev_b32_e32 v2, 16, v3
	v_and_b32_e32 v3, 0xffff0000, v3
	v_pk_mul_f32 v[42:43], v[20:21], v[20:21]
	v_pk_mul_f32 v[40:41], v[2:3], v[2:3]
	v_add_f32_e32 v0, v42, v43
	v_lshlrev_b32_e32 v34, 16, v4
	v_and_b32_e32 v35, 0xffff0000, v4
	v_add_f32_e32 v0, v40, v0
	v_pk_mul_f32 v[38:39], v[34:35], v[34:35]
	v_add_f32_e32 v0, v41, v0
	v_lshlrev_b32_e32 v4, 16, v5
	v_and_b32_e32 v5, 0xffff0000, v5
	v_add_f32_e32 v0, v38, v0
	v_pk_mul_f32 v[36:37], v[4:5], v[4:5]
	v_add_f32_e32 v0, v39, v0
	v_add_f32_e32 v0, v36, v0
	v_add_f32_e32 v0, v37, v0
	ds_bpermute_b32 v19, v24, v0
	s_waitcnt lgkmcnt(0)
	v_add_f32_e32 v0, v0, v19
	ds_bpermute_b32 v19, v25, v0
	s_waitcnt lgkmcnt(0)
	v_add_f32_e32 v0, v0, v19
	ds_bpermute_b32 v19, v26, v0
	s_waitcnt lgkmcnt(0)
	v_add_f32_e32 v0, v0, v19
	ds_bpermute_b32 v19, v27, v0
	s_waitcnt lgkmcnt(0)
	v_add_f32_e32 v0, v0, v19
	ds_bpermute_b32 v19, v28, v0
	s_waitcnt lgkmcnt(0)
	v_add_f32_e32 v0, v0, v19
	ds_bpermute_b32 v19, v29, v0
	s_waitcnt lgkmcnt(0)
	v_add_f32_e32 v0, v0, v19
	v_fmamk_f32 v0, v0, 0x3b000000, v201
	v_mul_f32_e32 v19, 0x4b800000, v0
	v_cmp_gt_f32_e32 vcc, s4, v0
	s_nop 1
	v_cndmask_b32_e32 v0, v0, v19, vcc
	v_rsq_f32_e32 v0, v0
	v_ashrrev_i32_e32 v19, 2, v32
	v_mul_f32_e32 v32, 0x45800000, v0
	v_cndmask_b32_e32 v0, v0, v32, vcc
	v_pk_mul_f32 v[6:7], v[60:61], v[0:1] op_sel_hi:[1,0]
	v_pk_mul_f32 v[8:9], v[62:63], v[0:1] op_sel_hi:[1,0]
	v_pk_mul_f32 v[10:11], v[64:65], v[0:1] op_sel_hi:[1,0]
	v_pk_mul_f32 v[12:13], v[66:67], v[0:1] op_sel_hi:[1,0]
	v_pk_mul_f32 v[6:7], v[6:7], v[20:21]
	v_pk_mul_f32 v[8:9], v[8:9], v[2:3]
	v_pk_mul_f32 v[10:11], v[10:11], v[34:35]
	v_pk_mul_f32 v[12:13], v[12:13], v[4:5]
	v_cvt_pk_bf16_f32 v2, v6, v7
	v_cvt_pk_bf16_f32 v3, v8, v9
	v_cvt_pk_bf16_f32 v4, v10, v11
	v_cvt_pk_bf16_f32 v5, v12, v13
	v_mad_i64_i32 v[6:7], s[40:41], v19, s96, v[22:23]
	global_store_dwordx4 v[6:7], v[2:5], off
	s_branch .LBB0_995

; DI unsigned pk2(float lo, float hi) { f32x2 v = {lo, hi}; bf2_t r = __builtin_convertvector(v, bf2_t); return __builtin_bit_cast(unsigned, r); }
; DI void ssd_scan_phase(bf16_t* P, const bf16_t* BT, const bf16_t* Cc, const bf16_t* CB, const float* dt, const float* acs,
;                        const float* cw, const float* cb, const float* Dp, char* lds, bool dry, int mode, float* Sbuf) {
;     ...
;     if (zero_init) { for (int q = tid; q < 2048; q += 512) ((unsigned*)sSt)[q] = 0u; }
;     else if (wave >= 4) {
;       float dsum = 0.f;
;       for (int cc = 16; cc < 32; ++cc) dsum += acs[((size_t)b * SEQ + cc * 128 + 127) * 32 + hh];
;       const float Db = __expf(dsum);
;       const float* spa = Sbuf + ((size_t)item * 4 + (wave - 4)) * 1024 + lane * 16;
;       const float* spb = spa + (size_t)128 * 4 * 1024;
; #pragma unroll
;       for (int gi = 0; gi < 4; ++gi) { const f32x4 va = *(const f32x4*)(spa + 4 * gi), vb = *(const f32x4*)(spb + 4 * gi); const f32x4 v = va * Db + vb;
;         st[4 * gi] = v[0]; st[4 * gi + 1] = v[1]; st[4 * gi + 2] = v[2]; st[4 * gi + 3] = v[3];
;         u32x2 ov; ov[0] = pk2(v[0], v[1]); ov[1] = pk2(v[2], v[3]);
;         *(u32x2*)(sSt + l31 * 256 + (((4 * (wave - 4) + gi) ^ (l31 & 15)) << 4) + 8 * h) = ov; }
;     }
.LBB0_1012:
	s_cmpk_gt_u32 s68, 0x7f
	s_cselect_b64 s[70:71], -1, 0
	s_and_b32 s69, s68, 3
	s_lshl_b32 s34, s69, 3
	s_bfe_u32 s56, s68, 0x30004
	s_or_b32 s72, s34, s56
	s_lshl_b32 s74, s72, 2
	v_mov_b32_e32 v0, s74
	global_load_dword v156, v0, s[58:59]
	s_xor_b64 s[76:77], s[62:63], -1
	s_and_b64 s[70:71], s[76:77], s[70:71]
	s_lshl_b32 s73, s68, 2
	s_mov_b64 s[56:57], -1
	s_bfe_u32 s34, s68, 0x10002
	s_and_b64 vcc, exec, s[70:71]
	s_cbranch_vccz .LBB0_1016
	v_mov_b32_e32 v4, v1
	v_mov_b32_e32 v5, v1
	v_mov_b32_e32 v6, v1
	v_mov_b32_e32 v7, v1
	v_mov_b32_e32 v8, v1
	v_mov_b32_e32 v9, v1
	s_waitcnt lgkmcnt(0)
	v_mov_b32_e32 v10, v1
	v_mov_b32_e32 v11, v1
	v_mov_b32_e32 v12, v1
	v_mov_b32_e32 v13, v1
	v_mov_b32_e32 v14, v1
	v_mov_b32_e32 v15, v1
	v_mov_b32_e32 v0, v1
	s_waitcnt vmcnt(1)
	v_mov_b32_e32 v2, v1
	v_mov_b32_e32 v3, v1
	v_mov_b64_e32 v[18:19], v[14:15]
	v_mov_b64_e32 v[16:17], v[12:13]
	v_mov_b64_e32 v[14:15], v[10:11]
	v_mov_b64_e32 v[12:13], v[8:9]
	v_mov_b64_e32 v[10:11], v[6:7]
	v_mov_b64_e32 v[8:9], v[4:5]
	v_mov_b64_e32 v[6:7], v[2:3]
	v_mov_b64_e32 v[4:5], v[0:1]
	s_and_saveexec_b64 s[56:57], s[42:43]
	s_cbranch_execz .LBB0_1015
	s_lshl_b32 s70, s34, 20
	s_or_b32 s70, s70, s74
	s_add_u32 s70, s26, s70
	s_addc_u32 s71, s27, 0
	v_mov_b32_e32 v2, 0x43000
	global_load_dword v20, v2, s[70:71] offset:3968
	v_mov_b32_e32 v2, 0x47000
	global_load_dword v21, v2, s[70:71] offset:3968
	v_mov_b32_e32 v2, 0x4b000
	global_load_dword v22, v2, s[70:71] offset:3968
	v_mov_b32_e32 v2, 0x4f000
	global_load_dword v23, v2, s[70:71] offset:3968
	v_mov_b32_e32 v2, 0x53000
	global_load_dword v24, v2, s[70:71] offset:3968
	v_mov_b32_e32 v2, 0x57000
	global_load_dword v25, v2, s[70:71] offset:3968
	v_mov_b32_e32 v2, 0x5b000
	global_load_dword v26, v2, s[70:71] offset:3968
	v_mov_b32_e32 v2, 0x5f000
	global_load_dword v27, v2, s[70:71] offset:3968
	v_mov_b32_e32 v2, 0x63000
	global_load_dword v28, v2, s[70:71] offset:3968
	v_mov_b32_e32 v2, 0x67000
	global_load_dword v29, v2, s[70:71] offset:3968
	v_mov_b32_e32 v2, 0x6b000
	global_load_dword v30, v2, s[70:71] offset:3968
	v_mov_b32_e32 v2, 0x6f000
	global_load_dword v31, v2, s[70:71] offset:3968
	v_mov_b32_e32 v2, 0x73000
	global_load_dword v32, v2, s[70:71] offset:3968
	v_mov_b32_e32 v2, 0x77000
	global_load_dword v33, v2, s[70:71] offset:3968
	v_mov_b32_e32 v2, 0x7b000
	global_load_dword v34, v2, s[70:71] offset:3968
	v_mov_b32_e32 v2, 0x7f000
	global_load_dword v35, v2, s[70:71] offset:3968
	s_and_b32 s70, s73, 0x1fc
	s_waitcnt vmcnt(0)
	v_add_f32_e32 v0, 0, v20
	v_add_f32_e32 v0, v0, v21
	v_add_f32_e32 v0, v0, v22
	v_add_f32_e32 v0, v0, v23
	v_add_f32_e32 v0, v0, v24
	v_add_f32_e32 v0, v0, v25
	v_add_f32_e32 v0, v0, v26
	v_add_f32_e32 v0, v0, v27
	v_add_f32_e32 v0, v0, v28
	v_add_f32_e32 v0, v0, v29
	v_add_f32_e32 v0, v0, v30
	v_add_f32_e32 v0, v0, v31
	v_add_f32_e32 v0, v0, v32
	v_add_f32_e32 v0, v0, v33
	v_add_f32_e32 v0, v0, v34
	v_add_f32_e32 v0, v0, v35
	v_mul_f32_e32 v0, 0x3fb8aa3b, v0
	v_exp_f32_e32 v36, v0
	v_add_u32_e32 v0, s70, v120
	v_lshlrev_b64 v[2:3], 12, v[0:1]
	v_lshl_add_u64 v[6:7], v[122:123], 0, v[2:3]
	s_mov_b64 s[70:71], 0x200000
	v_lshl_add_u64 v[32:33], v[6:7], 0, s[70:71]
	s_mov_b32 s70, 0x200000
	global_load_dwordx4 v[16:19], v[6:7], off offset:48
	global_load_dwordx4 v[12:15], v[6:7], off offset:32
	global_load_dwordx4 v[8:11], v[6:7], off offset:16
	global_load_dwordx4 v[2:5], v[6:7], off
	v_add_co_u32_e32 v6, vcc, s70, v6
	v_add_u32_e32 v0, v180, v121
	s_nop 0
	v_addc_co_u32_e32 v7, vcc, 0, v7, vcc
	global_load_dwordx4 v[20:23], v[6:7], off
	global_load_dwordx4 v[24:27], v[32:33], off offset:48
	global_load_dwordx4 v[28:31], v[32:33], off offset:32
	s_nop 0
	global_load_dwordx4 v[32:35], v[32:33], off offset:16
	s_waitcnt vmcnt(3)
	v_pk_fma_f32 v[6:7], v[4:5], v[36:37], v[22:23] op_sel_hi:[1,0,1]
	v_pk_fma_f32 v[4:5], v[2:3], v[36:37], v[20:21] op_sel_hi:[1,0,1]
	v_cvt_pk_bf16_f32 v3, v6, v7
	v_cvt_pk_bf16_f32 v2, v4, v5
	s_waitcnt vmcnt(0)
	v_pk_fma_f32 v[10:11], v[10:11], v[36:37], v[34:35] op_sel_hi:[1,0,1]
	v_pk_fma_f32 v[8:9], v[8:9], v[36:37], v[32:33] op_sel_hi:[1,0,1]
	ds_write_b64 v0, v[2:3]
	v_cvt_pk_bf16_f32 v2, v8, v9
	v_cvt_pk_bf16_f32 v3, v10, v11
	v_add_u32_e32 v0, v180, v188
	v_pk_fma_f32 v[14:15], v[36:37], v[14:15], v[30:31] op_sel_hi:[0,1,1]
	v_pk_fma_f32 v[12:13], v[36:37], v[12:13], v[28:29] op_sel_hi:[0,1,1]
	ds_write_b64 v0, v[2:3]
	v_cvt_pk_bf16_f32 v2, v12, v13
	v_cvt_pk_bf16_f32 v3, v14, v15
	v_add_u32_e32 v0, v180, v189
	v_pk_fma_f32 v[18:19], v[36:37], v[18:19], v[26:27] op_sel_hi:[0,1,1]
	v_pk_fma_f32 v[16:17], v[36:37], v[16:17], v[24:25] op_sel_hi:[0,1,1]
	ds_write_b64 v0, v[2:3]
	v_cvt_pk_bf16_f32 v2, v16, v17
	v_cvt_pk_bf16_f32 v3, v18, v19
	v_add_u32_e32 v0, v180, v190
	ds_write_b64 v0, v[2:3]

; #define MFMA(a, b, c) __builtin_amdgcn_mfma_f32_32x32x16_bf16((a), (b), (c), 0, 0, 0)
; DI unsigned pk2(float lo, float hi) { f32x2 v = {lo, hi}; bf2_t r = __builtin_convertvector(v, bf2_t); return __builtin_bit_cast(unsigned, r); }
; DI void pool_phase(const bf16_t* proj, bf16_t* cat, const bf16_t* Wp, const float* scale, char* lds) {
;     ...
;     for (int kk = 0; kk < 8; ++kk) {
;       const bf16x8 yf = *(const bf16x8*)(sD + swz128(32 * tk + l31, 2 * kk + h));
; #pragma unroll
;       for (int e = 0; e < 2; ++e) {
;         const bf16x8 xf = *(const bf16x8*)(sW + swz128(32 * (dt0 + e) + l31, 2 * kk + h));
;         acc[e] = MFMA(xf, yf, acc[e]);
;       }
;     }
;     const size_t tok = (size_t)t0 + 32 * tk + l31;
; #pragma unroll
;     for (int e = 0; e < 2; ++e)
; #pragma unroll
;       for (int gi = 0; gi < 4; ++gi) {
;         const int dout = 32 * (dt0 + e) + 8 * gi + 4 * h;
;         const f32x4 sc = *(const f32x4*)(scale + g * 128 + dout);
;         u32x2 ov; ov[0] = pk2(acc[e][4 * gi] * sc[0], acc[e][4 * gi + 1] * sc[1]); ov[1] = pk2(acc[e][4 * gi + 2] * sc[2], acc[e][4 * gi + 3] * sc[3]);
;         *(u32x2*)(cat + tok * 1024 + 512 + g * 128 + dout) = ov;
;       }
.LBB0_1145:
	v_add_u32_e32 v0, v116, v118
	s_waitcnt lgkmcnt(0)
	s_barrier
	ds_read_b128 v[2:5], v0
	v_add_u32_e32 v0, v119, v117
	ds_read_b128 v[6:9], v0 offset:32768
	v_add_u32_e32 v0, v119, v120
	s_ashr_i32 s0, s67, 31
	v_readlane_b32 s4, v252, 35
	v_readlane_b32 s5, v252, 36
	s_waitcnt lgkmcnt(0)
	v_mfma_f32_32x32x16_bf16 v[18:33], v[6:9], v[2:5], 0
	ds_read_b128 v[6:9], v0 offset:32768
	v_add_u32_e32 v0, v116, v121
	ds_read_b128 v[34:37], v0
	v_add_u32_e32 v0, v122, v117
	ds_read_b128 v[38:41], v0 offset:32768
	v_add_u32_e32 v0, v122, v120
	s_waitcnt lgkmcnt(0)
	v_mfma_f32_32x32x16_bf16 v[18:33], v[38:41], v[34:37], v[18:33]
	ds_read_b128 v[38:41], v0 offset:32768
	v_add_u32_e32 v0, v116, v123
	v_mfma_f32_32x32x16_bf16 v[2:17], v[6:9], v[2:5], 0
	s_waitcnt lgkmcnt(0)
	v_mfma_f32_32x32x16_bf16 v[2:17], v[38:41], v[34:37], v[2:17]
	ds_read_b128 v[34:37], v0
	v_add_u32_e32 v0, v124, v117
	ds_read_b128 v[38:41], v0 offset:32768
	v_add_u32_e32 v0, v124, v120
	s_waitcnt lgkmcnt(0)
	v_mfma_f32_32x32x16_bf16 v[18:33], v[38:41], v[34:37], v[18:33]
	ds_read_b128 v[38:41], v0 offset:32768
	v_add_u32_e32 v0, v116, v125
	s_waitcnt lgkmcnt(0)
	v_mfma_f32_32x32x16_bf16 v[2:17], v[38:41], v[34:37], v[2:17]
	ds_read_b128 v[34:37], v0
	v_add_u32_e32 v0, v126, v117
	ds_read_b128 v[38:41], v0 offset:32768
	v_add_u32_e32 v0, v126, v120
	s_waitcnt lgkmcnt(0)
	v_mfma_f32_32x32x16_bf16 v[18:33], v[38:41], v[34:37], v[18:33]
	ds_read_b128 v[38:41], v0 offset:32768
	v_add_u32_e32 v0, v116, v127
	s_waitcnt lgkmcnt(0)
	v_mfma_f32_32x32x16_bf16 v[2:17], v[38:41], v[34:37], v[2:17]
	ds_read_b128 v[34:37], v0
	v_add_u32_e32 v0, v128, v117
	ds_read_b128 v[38:41], v0 offset:32768
	v_add_u32_e32 v0, v128, v120
	s_waitcnt lgkmcnt(0)
	v_mfma_f32_32x32x16_bf16 v[18:33], v[38:41], v[34:37], v[18:33]
	ds_read_b128 v[38:41], v0 offset:32768
	v_add_u32_e32 v0, v116, v129
	s_waitcnt lgkmcnt(0)
	v_mfma_f32_32x32x16_bf16 v[2:17], v[38:41], v[34:37], v[2:17]
	ds_read_b128 v[34:37], v0
	v_add_u32_e32 v0, v130, v117
	ds_read_b128 v[38:41], v0 offset:32768
	v_add_u32_e32 v0, v130, v120
	s_waitcnt lgkmcnt(0)
	v_mfma_f32_32x32x16_bf16 v[18:33], v[38:41], v[34:37], v[18:33]
	ds_read_b128 v[38:41], v0 offset:32768
	v_add_u32_e32 v0, v116, v131
	s_waitcnt lgkmcnt(0)
	v_mfma_f32_32x32x16_bf16 v[2:17], v[38:41], v[34:37], v[2:17]
	ds_read_b128 v[34:37], v0
	v_add_u32_e32 v0, v132, v117
	ds_read_b128 v[38:41], v0 offset:32768
	v_add_u32_e32 v0, v132, v120
	s_waitcnt lgkmcnt(0)
	v_mfma_f32_32x32x16_bf16 v[18:33], v[38:41], v[34:37], v[18:33]
	ds_read_b128 v[38:41], v0 offset:32768
	v_add_u32_e32 v0, v116, v133
	s_waitcnt lgkmcnt(0)
	v_mfma_f32_32x32x16_bf16 v[2:17], v[38:41], v[34:37], v[2:17]
	ds_read_b128 v[34:37], v0
	v_add_u32_e32 v0, v142, v117
	ds_read_b128 v[38:41], v0 offset:32768
	v_add_u32_e32 v0, v142, v120
	s_waitcnt lgkmcnt(0)
	v_mfma_f32_32x32x16_bf16 v[18:33], v[38:41], v[34:37], v[18:33]
	ds_read_b128 v[38:41], v0 offset:32768
	s_waitcnt lgkmcnt(0)
	v_mfma_f32_32x32x16_bf16 v[2:17], v[38:41], v[34:37], v[2:17]
	v_mov_b32_e32 v35, s0
	s_lshl_b32 s0, s34, 9
	s_add_u32 s0, s30, s0
	s_addc_u32 s1, s31, 0
	v_lshl_add_u64 v[36:37], v[104:105], 2, s[0:1]
	v_lshl_add_u64 v[76:77], v[106:107], 2, s[0:1]
	global_load_dwordx4 v[44:47], v[36:37], off
	global_load_dwordx4 v[48:51], v[36:37], off offset:32
	global_load_dwordx4 v[52:55], v[36:37], off offset:64
	global_load_dwordx4 v[56:59], v[36:37], off offset:96
	global_load_dwordx4 v[60:63], v[76:77], off
	global_load_dwordx4 v[64:67], v[76:77], off offset:32
	global_load_dwordx4 v[68:71], v[76:77], off offset:64
	global_load_dwordx4 v[72:75], v[76:77], off offset:96
	v_or_b32_e32 v34, s67, v102
	v_lshlrev_b64 v[34:35], 11, v[34:35]
	v_lshl_add_u64 v[34:35], s[4:5], 0, v[34:35]
	s_lshl_b32 s34, s34, 8
	v_lshl_add_u64 v[34:35], v[34:35], 0, s[34:35]
	v_readlane_b32 s0, v252, 4
	v_readlane_b32 s1, v252, 5
	v_lshl_add_u64 v[38:39], v[104:105], 1, v[34:35]
	v_lshl_add_u64 v[78:79], v[106:107], 1, v[34:35]
	s_waitcnt vmcnt(7)
	v_pk_mul_f32 v[18:19], v[18:19], v[44:45]
	v_pk_mul_f32 v[20:21], v[20:21], v[46:47]
	v_cvt_pk_bf16_f32 v18, v18, v19
	v_cvt_pk_bf16_f32 v19, v20, v21
	global_store_dwordx2 v[38:39], v[18:19], off offset:1024
	s_waitcnt vmcnt(7)
	v_pk_mul_f32 v[22:23], v[22:23], v[48:49]
	v_pk_mul_f32 v[24:25], v[24:25], v[50:51]
	v_cvt_pk_bf16_f32 v22, v22, v23
	v_cvt_pk_bf16_f32 v23, v24, v25
	global_store_dwordx2 v[38:39], v[22:23], off offset:1040
	s_waitcnt vmcnt(7)
	v_pk_mul_f32 v[26:27], v[26:27], v[52:53]
	v_pk_mul_f32 v[28:29], v[28:29], v[54:55]
	v_cvt_pk_bf16_f32 v26, v26, v27
	v_cvt_pk_bf16_f32 v27, v28, v29
	global_store_dwordx2 v[38:39], v[26:27], off offset:1056
	s_waitcnt vmcnt(7)
	v_pk_mul_f32 v[30:31], v[30:31], v[56:57]
	v_pk_mul_f32 v[32:33], v[32:33], v[58:59]
	v_cvt_pk_bf16_f32 v30, v30, v31
	v_cvt_pk_bf16_f32 v31, v32, v33
	global_store_dwordx2 v[38:39], v[30:31], off offset:1072
	s_waitcnt vmcnt(7)
	v_pk_mul_f32 v[2:3], v[2:3], v[60:61]
	v_pk_mul_f32 v[4:5], v[4:5], v[62:63]
	v_cvt_pk_bf16_f32 v2, v2, v3
	v_cvt_pk_bf16_f32 v3, v4, v5
	global_store_dwordx2 v[78:79], v[2:3], off offset:1024
	s_waitcnt vmcnt(7)
	v_pk_mul_f32 v[6:7], v[6:7], v[64:65]
	v_pk_mul_f32 v[8:9], v[8:9], v[66:67]
	v_cvt_pk_bf16_f32 v6, v6, v7
	v_cvt_pk_bf16_f32 v7, v8, v9
	global_store_dwordx2 v[78:79], v[6:7], off offset:1040
	s_waitcnt vmcnt(7)
	v_pk_mul_f32 v[10:11], v[10:11], v[68:69]
	v_pk_mul_f32 v[12:13], v[12:13], v[70:71]
	v_cvt_pk_bf16_f32 v10, v10, v11
	v_cvt_pk_bf16_f32 v11, v12, v13
	global_store_dwordx2 v[78:79], v[10:11], off offset:1056
	s_waitcnt vmcnt(7)
	v_pk_mul_f32 v[14:15], v[14:15], v[72:73]
	v_pk_mul_f32 v[16:17], v[16:17], v[74:75]
	v_cvt_pk_bf16_f32 v14, v14, v15
	v_cvt_pk_bf16_f32 v15, v16, v17
	global_store_dwordx2 v[78:79], v[14:15], off offset:1072
	s_waitcnt lgkmcnt(0)
	s_barrier
	s_load_dword s0, s[0:1], 0x0
	s_waitcnt lgkmcnt(0)
	s_add_i32 s66, s0, s66
	s_cmpk_gt_i32 s66, 0x1ff
	s_cbranch_scc1 .LBB0_1160
